# combine chain: last block's C-term prefetch lands directly in its accumulator, loop-end rotation waits vmcnt(3) instead of a full drain
# speedup vs baseline: 1.0009x; 1.0009x over previous
; __device__ __forceinline__ void phase_combine(const Params& p, LAS unsigned char* lds, int tid, int lane, int wave, bool dummy) {
;     ...
;             for (int seg0 = 0; seg0 < 126; seg0 += 6) {
;                 CB_STEP(seg0 + 0, 0, true); CB_STEP(seg0 + 1, 1, true); CB_STEP(seg0 + 2, 2, true);
;                 CB_STEP(seg0 + 3, 3, true); CB_STEP(seg0 + 4, 4, true); CB_STEP(seg0 + 5, 5, true);
;             }
;             CB_STEP(126, 0, false);
.LBB0_508:
	s_min_u32 s2, s12, 0x72
	s_mul_i32 s10, s2, 0x18000
	s_mov_b32 s11, s73
	s_waitcnt lgkmcnt(0)
	s_barrier
	s_waitcnt vmcnt(16)
	ds_write_b128 v81, v[46:49]
	ds_write_b128 v81, v[42:45] offset:16
	v_lshl_add_u64 v[42:43], v[90:91], 0, s[10:11]
	s_mov_b64 s[10:11], 0x120000
	v_lshl_add_u64 v[44:45], v[42:43], 0, s[10:11]
	v_add_co_u32_e32 v42, vcc, 0x120000, v42
	v_lshl_add_u64 v[62:63], v[88:89], 0, s[72:73]
	s_nop 0
	v_addc_co_u32_e32 v43, vcc, 0, v43, vcc
	v_add_co_u32_e32 v62, vcc, 0x108000, v62
	global_load_dwordx4 v[46:49], v[42:43], off
	s_nop 0
	global_load_dwordx4 v[42:45], v[44:45], off offset:16
	v_addc_co_u32_e32 v63, vcc, 0, v63, vcc
	s_and_b64 vcc, exec, s[6:7]
	s_cbranch_vccnz .LBB0_510
	ds_read2st64_b32 v[200:201], v175 offset0:64 offset1:68
	ds_read2st64_b32 v[216:217], v176 offset0:144 offset1:145
	ds_read2st64_b32 v[202:203], v175 offset0:72 offset1:76
	ds_read2st64_b32 v[218:219], v176 offset0:146 offset1:147
	ds_read2st64_b32 v[204:205], v175 offset0:80 offset1:84
	ds_read2st64_b32 v[220:221], v176 offset0:148 offset1:149
	ds_read2st64_b32 v[206:207], v175 offset0:88 offset1:92
	ds_read2st64_b32 v[222:223], v176 offset0:150 offset1:151
	ds_read2st64_b32 v[208:209], v175 offset0:96 offset1:100
	ds_read2st64_b32 v[224:225], v176 offset0:152 offset1:153
	ds_read2st64_b32 v[210:211], v175 offset0:104 offset1:108
	ds_read2st64_b32 v[226:227], v176 offset0:154 offset1:155
	s_waitcnt vmcnt(16) lgkmcnt(10)
	v_mfma_f32_16x16x4_f32 v[54:57], v200, v216, v[54:57]
	v_mfma_f32_16x16x4_f32 v[94:97], v201, v217, 0
	ds_read2st64_b32 v[212:213], v175 offset0:112 offset1:116
	ds_read2st64_b32 v[228:229], v176 offset0:156 offset1:157
	s_waitcnt lgkmcnt(10)
	v_mfma_f32_16x16x4_f32 v[54:57], v202, v218, v[54:57]
	v_mfma_f32_16x16x4_f32 v[94:97], v203, v219, v[94:97]
	ds_read2st64_b32 v[214:215], v175 offset0:120 offset1:124
	ds_read2st64_b32 v[230:231], v176 offset0:158 offset1:159
	s_waitcnt lgkmcnt(10)
	v_mfma_f32_16x16x4_f32 v[54:57], v204, v220, v[54:57]
	v_mfma_f32_16x16x4_f32 v[94:97], v205, v221, v[94:97]
	s_waitcnt lgkmcnt(8)
	v_mfma_f32_16x16x4_f32 v[54:57], v206, v222, v[54:57]
	v_mfma_f32_16x16x4_f32 v[94:97], v207, v223, v[94:97]
	s_waitcnt lgkmcnt(6)
	v_mfma_f32_16x16x4_f32 v[54:57], v208, v224, v[54:57]
	v_mfma_f32_16x16x4_f32 v[94:97], v209, v225, v[94:97]
	s_waitcnt lgkmcnt(4)
	v_mfma_f32_16x16x4_f32 v[54:57], v210, v226, v[54:57]
	v_mfma_f32_16x16x4_f32 v[94:97], v211, v227, v[94:97]
	s_waitcnt lgkmcnt(2)
	v_mfma_f32_16x16x4_f32 v[54:57], v212, v228, v[54:57]
	v_mfma_f32_16x16x4_f32 v[94:97], v213, v229, v[94:97]
	s_waitcnt lgkmcnt(0)
	v_mfma_f32_16x16x4_f32 v[54:57], v214, v230, v[54:57]
	v_mfma_f32_16x16x4_f32 v[94:97], v215, v231, v[94:97]
	s_nop 9
	v_pk_add_f32 v[54:55], v[54:55], v[94:95]
	v_add_co_u32_e32 v94, vcc, 0x78000, v92
	v_pk_add_f32 v[56:57], v[56:57], v[96:97]
	s_nop 0
	v_addc_co_u32_e32 v95, vcc, 0, v93, vcc
	global_store_dwordx4 v[94:95], v[54:57], off
	ds_write2_b32 v0, v54, v55 offset1:16
	ds_write2_b32 v0, v56, v57 offset0:32 offset1:48
.LBB0_510:
	global_load_dwordx4 v[54:57], v[62:63], off
	s_waitcnt lgkmcnt(0)
	s_barrier
	v_lshl_add_u64 v[92:93], v[92:93], 0, s[88:89]
	s_cmpk_gt_u32 s12, 0x77
	s_cbranch_scc1 .LBB0_512
	s_waitcnt vmcnt(3)
	v_mov_b64_e32 v[62:63], v[70:71]
	v_mov_b64_e32 v[64:65], v[72:73]
	v_mov_b64_e32 v[70:71], v[74:75]
	v_mov_b64_e32 v[72:73], v[76:77]
	v_mov_b64_e32 v[76:77], v[68:69]
	v_mov_b64_e32 v[74:75], v[66:67]
	v_mov_b64_e32 v[68:69], v[60:61]
	v_mov_b64_e32 v[66:67], v[58:59]
	v_mov_b64_e32 v[60:61], v[52:53]
	v_mov_b64_e32 v[58:59], v[50:51]
	s_branch .LBB0_498
